# out-proj f32 epilogue rewritten (3 groups ahead) + attention: dropped vmcnt(0) before queue and sso atomics
# baseline (speedup 1.0000x reference)
; __device__ __forceinline__ void phase_attn(const Ctx& C, const float* relb  , int layer) {
;     ...
;           for (;;) {
;               unsigned idx = 0;
;               if (lane == 0) idx = __hip_atomic_fetch_add(qb_, 1u, __ATOMIC_RELAXED, __HIP_MEMORY_SCOPE_AGENT);
;               idx = (unsigned)__builtin_amdgcn_readfirstlane((int)idx);
;               if (idx >= (unsigned)per_q) break;
;               const int bh = x * 8 + (int)(idx >> 7), qi = 127 - (int)(idx & 127);
;               attnB_wave(st, QKV, O, sso, bh >> 3, bh & 7, qi, lane);
;           }
;           for (;;) {
;               unsigned idx = 0;
;               if (lane == 0) idx = __hip_atomic_fetch_add(qa_, 1u, __ATOMIC_RELAXED, __HIP_MEMORY_SCOPE_AGENT);
;               idx = (unsigned)__builtin_amdgcn_readfirstlane((int)idx);
;               if (idx >= (unsigned)per_q) break;
.LBB0_265:
	v_mov_b32_e32 v0, 0
	s_and_saveexec_b64 s[12:13], s[36:37]
	s_cbranch_execz .LBB0_267
	s_waitcnt lgkmcnt(0)
	v_mov_b64_e32 v[0:1], s[20:21]
	flat_atomic_add v0, v[0:1], v216 sc0

; __device__ __forceinline__ unsigned pk2(float lo, float hi) { return pg8::cvt_pk_bf16(lo, hi); }
; __device__ __forceinline__ void store_o(bf16* Op, const f32x16& o0, const f32x16& o1, float inv, int hi, float* ssrow) {
;     float p = 0.f;
; #pragma unroll
;     for (int u = 0; u < 4; ++u) {
;         const f32x4 a = (f32x4){o0[4 * u] * inv, o0[4 * u + 1] * inv, o0[4 * u + 2] * inv, o0[4 * u + 3] * inv}, c = (f32x4){o1[4 * u] * inv, o1[4 * u + 1] * inv, o1[4 * u + 2] * inv, o1[4 * u + 3] * inv};
;         p += ((a.x * a.x + a.y * a.y) + (a.z * a.z + a.w * a.w)) + ((c.x * c.x + c.y * c.y) + (c.z * c.z + c.w * c.w));
;         u32x2 w; w.x = pk2(a.x, a.y); w.y = pk2(a.z, a.w);
;         *(u32x2*)(Op + 8 * u + 4 * hi) = w;
;         u32x2 w1; w1.x = pk2(c.x, c.y); w1.y = pk2(c.z, c.w);
;         *(u32x2*)(Op + 32 + 8 * u + 4 * hi) = w1;
;     }
;     p += __shfl_xor(p, 32);
;     if (hi == 0) atomicAdd(ssrow, p);
; }
; __device__ __forceinline__ void attnB_wave(LAS unsigned char* st, const bf16* QKV, bf16* O, float* sso, int b, int h, int qi, int lane) {
;     ...
;     asm volatile("s_waitcnt vmcnt(0) lgkmcnt(0)" ::: "memory");
;     store_o(O + (tb + q0 + ql) * 1024 + 512 + h * 64, S.o0, S.o1, 1.0f, hi, sso + T + tb + q0 + ql);
.LBB0_297:
	v_lshlrev_b32_e32 v80, 11, v80
	v_lshl_add_u64 v[0:1], s[4:5], 0, v[80:81]
	s_mov_b32 s13, s11
	v_lshl_add_u64 v[0:1], v[0:1], 0, s[12:13]
	v_lshl_add_u64 v[2:3], v[126:127], 1, v[0:1]
	s_nop 4
	v_mul_f32_e32 v0, v33, v33
	v_mul_f32_e32 v1, v35, v35
	v_fmac_f32_e32 v0, v32, v32
	v_fmac_f32_e32 v1, v34, v34
	v_add_f32_e32 v0, v0, v1
	v_mul_f32_e32 v1, v17, v17
	v_mul_f32_e32 v4, v19, v19
	v_fmac_f32_e32 v1, v16, v16
	v_fmac_f32_e32 v4, v18, v18
	v_add_f32_e32 v1, v1, v4
	v_add_f32_e32 v4, v1, v0
	v_cvt_pk_bf16_f32 v0, v32, v33
	v_cvt_pk_bf16_f32 v1, v34, v35
	s_waitcnt vmcnt(0) lgkmcnt(0)
	flat_store_dwordx2 v[2:3], v[0:1] offset:1024
	v_cvt_pk_bf16_f32 v0, v16, v17
	v_cvt_pk_bf16_f32 v1, v18, v19
	flat_store_dwordx2 v[2:3], v[0:1] offset:1088
	v_mul_f32_e32 v0, v37, v37
	v_mul_f32_e32 v1, v39, v39
	v_fmac_f32_e32 v0, v36, v36
	v_fmac_f32_e32 v1, v38, v38
	v_add_f32_e32 v0, v0, v1
	v_mul_f32_e32 v1, v21, v21
	v_mul_f32_e32 v5, v23, v23
	v_fmac_f32_e32 v1, v20, v20
	v_fmac_f32_e32 v5, v22, v22
	v_add_f32_e32 v1, v1, v5
	v_add_f32_e32 v0, v1, v0
	v_add_f32_e32 v4, v4, v0
	v_cvt_pk_bf16_f32 v0, v36, v37
	v_cvt_pk_bf16_f32 v1, v38, v39
	flat_store_dwordx2 v[2:3], v[0:1] offset:1040
	v_cvt_pk_bf16_f32 v0, v20, v21
	v_cvt_pk_bf16_f32 v1, v22, v23
	flat_store_dwordx2 v[2:3], v[0:1] offset:1104
	v_mul_f32_e32 v0, v41, v41
	v_mul_f32_e32 v1, v43, v43
	v_fmac_f32_e32 v0, v40, v40
	v_fmac_f32_e32 v1, v42, v42
	v_add_f32_e32 v0, v0, v1
	v_mul_f32_e32 v1, v25, v25
	v_mul_f32_e32 v5, v27, v27
	v_fmac_f32_e32 v1, v24, v24
	v_fmac_f32_e32 v5, v26, v26
	v_add_f32_e32 v1, v1, v5
	v_add_f32_e32 v0, v1, v0
	v_add_f32_e32 v4, v0, v4
	v_cvt_pk_bf16_f32 v0, v40, v41
	v_cvt_pk_bf16_f32 v1, v42, v43
	flat_store_dwordx2 v[2:3], v[0:1] offset:1056
	v_cvt_pk_bf16_f32 v0, v24, v25
	v_cvt_pk_bf16_f32 v1, v26, v27
	flat_store_dwordx2 v[2:3], v[0:1] offset:1120
	v_mul_f32_e32 v0, v45, v45
	v_mul_f32_e32 v1, v47, v47
	v_fmac_f32_e32 v0, v44, v44
	v_fmac_f32_e32 v1, v46, v46
	v_add_f32_e32 v0, v0, v1
	v_mul_f32_e32 v1, v29, v29
	v_mul_f32_e32 v5, v31, v31
	v_fmac_f32_e32 v1, v28, v28
	v_fmac_f32_e32 v5, v30, v30
	v_add_f32_e32 v1, v1, v5
	v_add_f32_e32 v0, v1, v0
	v_add_f32_e32 v0, v0, v4
	ds_bpermute_b32 v1, v112, v0
	v_cvt_pk_bf16_f32 v4, v44, v45
	v_cvt_pk_bf16_f32 v5, v46, v47
	flat_store_dwordx2 v[2:3], v[4:5] offset:1072
	v_cvt_pk_bf16_f32 v4, v28, v29
	v_cvt_pk_bf16_f32 v5, v30, v31
	flat_store_dwordx2 v[2:3], v[4:5] offset:1136
	s_and_saveexec_b64 s[12:13], s[38:39]
	s_xor_b64 s[12:13], exec, s[12:13]
	s_cbranch_execz .LBB0_263
	s_lshl_b32 s10, s80, 2
	s_waitcnt lgkmcnt(0)
	v_add_f32_e32 v2, v0, v1
	v_lshl_add_u64 v[0:1], v[100:101], 0, s[10:11]
	flat_atomic_add_f32 v[0:1], v2
	s_branch .LBB0_263

; __device__ __forceinline__ unsigned pk2(float lo, float hi) { return pg8::cvt_pk_bf16(lo, hi); }
; __device__ __forceinline__ void store_o(bf16* Op, const f32x16& o0, const f32x16& o1, float inv, int hi, float* ssrow) {
;     float p = 0.f;
; #pragma unroll
;     for (int u = 0; u < 4; ++u) {
;         const f32x4 a = (f32x4){o0[4 * u] * inv, o0[4 * u + 1] * inv, o0[4 * u + 2] * inv, o0[4 * u + 3] * inv}, c = (f32x4){o1[4 * u] * inv, o1[4 * u + 1] * inv, o1[4 * u + 2] * inv, o1[4 * u + 3] * inv};
;         p += ((a.x * a.x + a.y * a.y) + (a.z * a.z + a.w * a.w)) + ((c.x * c.x + c.y * c.y) + (c.z * c.z + c.w * c.w));
;         u32x2 w; w.x = pk2(a.x, a.y); w.y = pk2(a.z, a.w);
;         *(u32x2*)(Op + 8 * u + 4 * hi) = w;
;         u32x2 w1; w1.x = pk2(c.x, c.y); w1.y = pk2(c.z, c.w);
;         *(u32x2*)(Op + 32 + 8 * u + 4 * hi) = w1;
;     }
;     p += __shfl_xor(p, 32);
;     if (hi == 0) atomicAdd(ssrow, p);
; }
; __device__ __forceinline__ void attnA_wave(LAS unsigned char* st, const LAS float* tb2, const bf16* QKV, bf16* O, float* sso, int b, int h, int qblk, int lane) {
;     ...
;     asm volatile("s_waitcnt vmcnt(0) lgkmcnt(0)" ::: "memory");
;     S.l += __shfl_xor(S.l, 32);
;     store_o(O + (tb + q0 + ql) * 1024 + h * 64, S.o0, S.o1, 1.0f / S.l, hi, sso + tb + q0 + ql);
.LBB0_327:
	s_lshl_b32 s3, s80, 6
	s_mov_b32 s86, 0x3fb8aa3b
	v_cmp_lt_i32_e32 vcc, v208, v207
	v_lshlrev_b32_e32 v80, 11, v156
	s_lshl_b32 s10, s3, 1
	v_cndmask_b32_e32 v32, v206, v208, vcc
	v_lshlrev_b32_e32 v35, 2, v32
	ds_bpermute_b32 v32, v35, v65
	s_waitcnt vmcnt(0) lgkmcnt(0)
	s_waitcnt lgkmcnt(0)
	v_add_f32_e32 v34, v65, v32
	v_div_scale_f32 v36, s[12:13], v34, v34, 1.0
	v_rcp_f32_e32 v37, v36
	v_lshl_add_u64 v[32:33], s[4:5], 0, v[80:81]
	v_lshl_add_u64 v[32:33], v[32:33], 0, s[10:11]
	v_lshl_add_u64 v[32:33], v[126:127], 1, v[32:33]
	v_fma_f32 v38, -v36, v37, 1.0
	v_fmac_f32_e32 v37, v38, v37
	v_div_scale_f32 v38, vcc, 1.0, v34, 1.0
	v_mul_f32_e32 v39, v38, v37
	v_fma_f32 v40, -v36, v39, v38
	v_fmac_f32_e32 v39, v40, v37
	v_fma_f32 v36, -v36, v39, v38
	v_div_fmas_f32 v36, v36, v37, v39
	v_div_fixup_f32 v34, v36, v34, 1.0
	v_pk_mul_f32 v[0:1], v[0:1], v[34:35] op_sel_hi:[1,0]
	v_pk_mul_f32 v[2:3], v[2:3], v[34:35] op_sel_hi:[1,0]
	v_pk_mul_f32 v[16:17], v[16:17], v[34:35] op_sel_hi:[1,0]
	v_pk_mul_f32 v[18:19], v[18:19], v[34:35] op_sel_hi:[1,0]
	v_pk_mul_f32 v[36:37], v[0:1], v[0:1]
	v_cvt_pk_bf16_f32 v0, v0, v1
	v_cvt_pk_bf16_f32 v1, v2, v3
	flat_store_dwordx2 v[32:33], v[0:1]
	v_cvt_pk_bf16_f32 v0, v16, v17
	v_cvt_pk_bf16_f32 v1, v18, v19
	v_pk_mul_f32 v[38:39], v[2:3], v[2:3]
	flat_store_dwordx2 v[32:33], v[0:1] offset:64
	v_pk_mul_f32 v[0:1], v[4:5], v[34:35] op_sel_hi:[1,0]
	v_pk_mul_f32 v[2:3], v[6:7], v[34:35] op_sel_hi:[1,0]
	v_pk_mul_f32 v[40:41], v[16:17], v[16:17]
	v_pk_mul_f32 v[42:43], v[18:19], v[18:19]
	v_pk_mul_f32 v[4:5], v[20:21], v[34:35] op_sel_hi:[1,0]
	v_pk_mul_f32 v[6:7], v[22:23], v[34:35] op_sel_hi:[1,0]
	v_pk_mul_f32 v[16:17], v[0:1], v[0:1]
	v_pk_mul_f32 v[18:19], v[2:3], v[2:3]
	v_cvt_pk_bf16_f32 v0, v0, v1
	v_cvt_pk_bf16_f32 v1, v2, v3
	flat_store_dwordx2 v[32:33], v[0:1] offset:16
	v_cvt_pk_bf16_f32 v0, v4, v5
	v_cvt_pk_bf16_f32 v1, v6, v7
	v_add_f32_e32 v18, v18, v19
	v_add_f32_e32 v16, v16, v17
	v_pk_mul_f32 v[20:21], v[4:5], v[4:5]
	v_pk_mul_f32 v[22:23], v[6:7], v[6:7]
	flat_store_dwordx2 v[32:33], v[0:1] offset:80
	v_pk_mul_f32 v[0:1], v[8:9], v[34:35] op_sel_hi:[1,0]
	v_pk_mul_f32 v[2:3], v[10:11], v[34:35] op_sel_hi:[1,0]
	v_add_f32_e32 v16, v16, v18
	v_add_f32_e32 v17, v42, v43
	v_add_f32_e32 v18, v40, v41
	v_pk_mul_f32 v[6:7], v[26:27], v[34:35] op_sel_hi:[1,0]
	v_pk_mul_f32 v[8:9], v[0:1], v[0:1]
	v_cvt_pk_bf16_f32 v0, v0, v1
	v_cvt_pk_bf16_f32 v1, v2, v3
	v_add_f32_e32 v22, v22, v23
	v_add_f32_e32 v20, v20, v21
	v_add_f32_e32 v17, v18, v17
	v_add_f32_e32 v18, v38, v39
	v_add_f32_e32 v19, v36, v37
	v_pk_mul_f32 v[4:5], v[24:25], v[34:35] op_sel_hi:[1,0]
	v_pk_mul_f32 v[10:11], v[2:3], v[2:3]
	v_pk_mul_f32 v[26:27], v[6:7], v[6:7]
	flat_store_dwordx2 v[32:33], v[0:1] offset:32
	v_cvt_pk_bf16_f32 v1, v6, v7
	v_pk_mul_f32 v[2:3], v[12:13], v[34:35] op_sel_hi:[1,0]
	v_pk_mul_f32 v[6:7], v[28:29], v[34:35] op_sel_hi:[1,0]
	v_pk_mul_f32 v[12:13], v[30:31], v[34:35] op_sel_hi:[1,0]
	v_add_f32_e32 v20, v20, v22
	v_add_f32_e32 v18, v19, v18
	v_pk_mul_f32 v[24:25], v[4:5], v[4:5]
	v_cvt_pk_bf16_f32 v0, v4, v5
	v_pk_mul_f32 v[4:5], v[14:15], v[34:35] op_sel_hi:[1,0]
	v_pk_mul_f32 v[28:29], v[6:7], v[6:7]
	v_pk_mul_f32 v[30:31], v[12:13], v[12:13]
	v_add_f32_e32 v16, v16, v20
	v_add_f32_e32 v17, v18, v17
	v_add_f32_e32 v10, v10, v11
	v_add_f32_e32 v8, v8, v9
	flat_store_dwordx2 v[32:33], v[0:1] offset:96
	v_pk_mul_f32 v[0:1], v[2:3], v[2:3]
	v_pk_mul_f32 v[14:15], v[4:5], v[4:5]
	v_add_f32_e32 v16, v17, v16
	v_add_f32_e32 v17, v26, v27
	v_add_f32_e32 v18, v24, v25
	v_add_f32_e32 v8, v8, v10
	v_add_f32_e32 v9, v30, v31
	v_add_f32_e32 v10, v28, v29
	v_add_f32_e32 v17, v18, v17
	v_add_f32_e32 v9, v10, v9
	v_add_f32_e32 v10, v14, v15
	v_add_f32_e32 v0, v0, v1
	v_add_f32_e32 v8, v8, v17
	v_add_f32_e32 v0, v0, v10
	v_add_f32_e32 v8, v8, v16
	v_add_f32_e32 v0, v0, v9
	v_add_f32_e32 v0, v0, v8
	ds_bpermute_b32 v1, v35, v0
	v_cvt_pk_bf16_f32 v2, v2, v3
	v_cvt_pk_bf16_f32 v3, v4, v5
	flat_store_dwordx2 v[32:33], v[2:3] offset:48
	v_cvt_pk_bf16_f32 v2, v6, v7
	v_cvt_pk_bf16_f32 v3, v12, v13
	flat_store_dwordx2 v[32:33], v[2:3] offset:112
	s_and_saveexec_b64 s[12:13], s[38:39]
	s_xor_b64 s[12:13], exec, s[12:13]
	s_cbranch_execz .LBB0_300
	s_lshl_b32 s10, s2, 2
	s_waitcnt lgkmcnt(0)
	v_add_f32_e32 v2, v0, v1
	v_lshl_add_u64 v[0:1], v[140:141], 0, s[10:11]
	flat_atomic_add_f32 v[0:1], v2
	s_branch .LBB0_300

; __device__ __forceinline__ unsigned cvt_pk_bf16(float lo, float hi) { f32x2_cv v = {lo, hi}; bf16x2_cv b = __builtin_convertvector(v, bf16x2_cv); return __builtin_bit_cast(unsigned, b); }
;     __device__ __forceinline__ void operator()(const f32x4 (&acc)[2][2][4][2], const Unit& u, int wr, int wc, int fr, int fq) const {
;         const int row0 = u.pm * BM + wr * 64 + fr; const int col0 = u.pn * BM + wc * 32 + 8 * fq;
;         const int b = (u.pm * BM) >> 12;
;         f32x4 gv[2][2];
; #pragma unroll
;         for (int bj = 0; bj < 2; ++bj)
; #pragma unroll
;             for (int n = 0; n < 2; ++n) gv[bj][n] = *(const f32x4*)(gate + (size_t)b * gate_ld + col0 + bj * HALF + n * 4);
;         f32x4 xv[2][2][2];
;         load_x(xv[0], (size_t)row0 * 1024 + col0);
; #pragma unroll
;         for (int g = 0; g < 8; ++g) { const int ai = g >> 2, m = g & 3; const size_t off = (size_t)(row0 + ai * HALF + m * 16) * 1024 + col0;
;             if (g + 1 < 8) { const int ai2 = (g + 1) >> 2, m2 = (g + 1) & 3; load_x(xv[(g + 1) & 1], (size_t)(row0 + ai2 * HALF + m2 * 16) * 1024 + col0); }
;             float rs_ = 1.0f; if constexpr (ROWSCALE) rs_ = tab[((u.pm == pm0 ? 0 : 256) + ai * HALF + wr * 64 + m * 16 + fr) * 2 + 1];
; #pragma unroll
;             for (int bj = 0; bj < 2; ++bj) { const f32x4 v0 = xv[g & 1][bj][0] + gv[bj][0] * (acc[ai][bj][m][0] * rs_), v1 = xv[g & 1][bj][1] + gv[bj][1] * (acc[ai][bj][m][1] * rs_);
;                 u32x4 w; w.x = cvt_pk_bf16(v0[0], v0[1]); w.y = cvt_pk_bf16(v0[2], v0[3]); w.z = cvt_pk_bf16(v1[0], v1[1]); w.w = cvt_pk_bf16(v1[2], v1[3]);
;                 *(u32x4*)(out + off + bj * HALF) = w; } }
.LBB0_445:
	s_ashr_i32 s3, s4, 4
	v_lshl_or_b32 v205, s5, 8, v191
	s_mul_hi_i32 s5, s3, 0x6000
	s_mulk_i32 s3, 0x6000
	v_readlane_b32 s80, v254, 4
	s_add_u32 s12, s64, s3
	v_readlane_b32 s81, v254, 5
	s_addc_u32 s13, s65, s5
	v_lshlrev_b32_e32 v211, 2, v205
	global_load_dwordx4 v[76:79], v211, s[12:13]
	global_load_dwordx4 v[72:75], v211, s[12:13] offset:16
	global_load_dwordx4 v[68:71], v211, s[12:13] offset:512
	global_load_dwordx4 v[64:67], v211, s[12:13] offset:528
	v_lshl_add_u32 v185, v186, 12, v211
	v_lshlrev_b32_e32 v195, 11, v186
	v_lshl_add_u32 v195, v205, 1, v195
	s_lshl_b32 s3, s4, 20
	s_add_u32 s98, s80, s3
	s_addc_u32 s99, s81, 0
	s_lshl_b32 s3, s4, 19
	s_add_u32 s100, s38, s3
	s_addc_u32 s101, s39, 0
	global_load_dwordx4 v[148:151], v185, s[98:99]
	global_load_dwordx4 v[152:155], v185, s[98:99] offset:16
	global_load_dwordx4 v[180:183], v185, s[98:99] offset:512
	global_load_dwordx4 v[196:199], v185, s[98:99] offset:528
	s_add_u32 s98, s98, 0x10000
	s_addc_u32 s99, s99, 0
	global_load_dwordx4 v[200:203], v185, s[98:99]
	global_load_dwordx4 v[220:223], v185, s[98:99] offset:16
	global_load_dwordx4 v[224:227], v185, s[98:99] offset:512
	global_load_dwordx4 v[228:231], v185, s[98:99] offset:528
	s_add_u32 s98, s98, 0x10000
	s_addc_u32 s99, s99, 0
	global_load_dwordx4 v[236:239], v185, s[98:99]
	global_load_dwordx4 v[240:243], v185, s[98:99] offset:16
	global_load_dwordx4 v[244:247], v185, s[98:99] offset:512
	global_load_dwordx4 v[248:251], v185, s[98:99] offset:528
	s_add_u32 s98, s98, 0x10000
	s_addc_u32 s99, s99, 0
	v_readlane_b32 s3, v255, 49
	s_nop 0
	s_cmp_eq_u32 s4, s3
	s_cselect_b32 s4, 0, 0x100
	v_add_u32_e32 v83, s4, v186
	s_add_i32 s5, 0, 0x22800
	v_lshl_add_u32 v83, v83, 3, s5
	s_andn2_b64 vcc, exec, s[36:37]
	s_mov_b32 s78, s1
	v_readlane_b32 s82, v254, 6
	v_readlane_b32 s83, v254, 7
	v_readlane_b32 s84, v254, 8
	v_readlane_b32 s85, v254, 9
	v_readlane_b32 s86, v254, 10
	v_readlane_b32 s87, v254, 11
	v_readlane_b32 s88, v254, 12
	v_readlane_b32 s89, v254, 13
	v_readlane_b32 s90, v254, 14
	v_readlane_b32 s91, v254, 15
	v_readlane_b32 s92, v254, 16
	v_readlane_b32 s93, v254, 17
	v_readlane_b32 s94, v254, 18
	v_readlane_b32 s95, v254, 19
	ds_read_b32 v184, v83 offset:4
	ds_read_b32 v194, v83 offset:132
	ds_read_b32 v204, v83 offset:260
	ds_read_b32 v210, v83 offset:388
	ds_read_b32 v232, v83 offset:1028
	ds_read_b32 v234, v83 offset:1156
	ds_read_b32 v82, v83 offset:1284
	ds_read_b32 v80, v83 offset:1412
	s_waitcnt lgkmcnt(0)
	s_waitcnt vmcnt(8)
	v_pk_mul_f32 v[144:145], v[144:145], v[184:185] op_sel_hi:[1,0]
	v_pk_mul_f32 v[146:147], v[146:147], v[184:185] op_sel_hi:[1,0]
	v_pk_mul_f32 v[140:141], v[140:141], v[184:185] op_sel_hi:[1,0]
	v_pk_mul_f32 v[142:143], v[142:143], v[184:185] op_sel_hi:[1,0]
	v_pk_fma_f32 v[144:145], v[76:77], v[144:145], v[148:149]
	v_pk_fma_f32 v[146:147], v[78:79], v[146:147], v[150:151]
	v_pk_fma_f32 v[140:141], v[72:73], v[140:141], v[152:153]
	v_pk_fma_f32 v[142:143], v[74:75], v[142:143], v[154:155]
	v_cvt_pk_bf16_f32 v148, v144, v145
	v_cvt_pk_bf16_f32 v149, v146, v147
	v_cvt_pk_bf16_f32 v150, v140, v141
	v_cvt_pk_bf16_f32 v151, v142, v143
	global_store_dwordx4 v195, v[148:151], s[100:101]
	v_pk_mul_f32 v[136:137], v[136:137], v[184:185] op_sel_hi:[1,0]
	v_pk_mul_f32 v[138:139], v[138:139], v[184:185] op_sel_hi:[1,0]
	v_pk_mul_f32 v[132:133], v[132:133], v[184:185] op_sel_hi:[1,0]
	v_pk_mul_f32 v[134:135], v[134:135], v[184:185] op_sel_hi:[1,0]
	v_pk_fma_f32 v[136:137], v[68:69], v[136:137], v[180:181]
	v_pk_fma_f32 v[138:139], v[70:71], v[138:139], v[182:183]
	v_pk_fma_f32 v[132:133], v[64:65], v[132:133], v[196:197]
	v_pk_fma_f32 v[134:135], v[66:67], v[134:135], v[198:199]
	v_cvt_pk_bf16_f32 v180, v136, v137
	v_cvt_pk_bf16_f32 v181, v138, v139
	v_cvt_pk_bf16_f32 v182, v132, v133
	v_cvt_pk_bf16_f32 v183, v134, v135
	global_store_dwordx4 v195, v[180:183], s[100:101] offset:256
	s_add_u32 s100, s100, 0x8000
	s_addc_u32 s101, s101, 0
	global_load_dwordx4 v[148:151], v185, s[98:99]
	global_load_dwordx4 v[152:155], v185, s[98:99] offset:16
	global_load_dwordx4 v[180:183], v185, s[98:99] offset:512
	global_load_dwordx4 v[196:199], v185, s[98:99] offset:528
	s_add_u32 s98, s98, 0x50000
	s_addc_u32 s99, s99, 0
	s_waitcnt vmcnt(10)
	v_pk_mul_f32 v[128:129], v[128:129], v[194:195] op_sel_hi:[1,0]
	v_pk_mul_f32 v[130:131], v[130:131], v[194:195] op_sel_hi:[1,0]
	v_pk_mul_f32 v[124:125], v[124:125], v[194:195] op_sel_hi:[1,0]
	v_pk_mul_f32 v[126:127], v[126:127], v[194:195] op_sel_hi:[1,0]
	v_pk_fma_f32 v[128:129], v[76:77], v[128:129], v[200:201]
	v_pk_fma_f32 v[130:131], v[78:79], v[130:131], v[202:203]
	v_pk_fma_f32 v[124:125], v[72:73], v[124:125], v[220:221]
	v_pk_fma_f32 v[126:127], v[74:75], v[126:127], v[222:223]
	v_cvt_pk_bf16_f32 v200, v128, v129
	v_cvt_pk_bf16_f32 v201, v130, v131
	v_cvt_pk_bf16_f32 v202, v124, v125
	v_cvt_pk_bf16_f32 v203, v126, v127
	global_store_dwordx4 v195, v[200:203], s[100:101]
	v_pk_mul_f32 v[120:121], v[120:121], v[194:195] op_sel_hi:[1,0]
	v_pk_mul_f32 v[122:123], v[122:123], v[194:195] op_sel_hi:[1,0]
	v_pk_mul_f32 v[116:117], v[116:117], v[194:195] op_sel_hi:[1,0]
	v_pk_mul_f32 v[118:119], v[118:119], v[194:195] op_sel_hi:[1,0]
	v_pk_fma_f32 v[120:121], v[68:69], v[120:121], v[224:225]
	v_pk_fma_f32 v[122:123], v[70:71], v[122:123], v[226:227]
	v_pk_fma_f32 v[116:117], v[64:65], v[116:117], v[228:229]
	v_pk_fma_f32 v[118:119], v[66:67], v[118:119], v[230:231]
	v_cvt_pk_bf16_f32 v224, v120, v121
	v_cvt_pk_bf16_f32 v225, v122, v123
	v_cvt_pk_bf16_f32 v226, v116, v117
	v_cvt_pk_bf16_f32 v227, v118, v119
	global_store_dwordx4 v195, v[224:227], s[100:101] offset:256
	s_add_u32 s100, s100, 0x8000
	s_addc_u32 s101, s101, 0
	global_load_dwordx4 v[200:203], v185, s[98:99]
	global_load_dwordx4 v[220:223], v185, s[98:99] offset:16
	global_load_dwordx4 v[224:227], v185, s[98:99] offset:512
	global_load_dwordx4 v[228:231], v185, s[98:99] offset:528
	s_add_u32 s98, s98, 0x10000
	s_addc_u32 s99, s99, 0
	s_waitcnt vmcnt(12)
; __device__ __forceinline__ unsigned cvt_pk_bf16(float lo, float hi) { f32x2_cv v = {lo, hi}; bf16x2_cv b = __builtin_convertvector(v, bf16x2_cv); return __builtin_bit_cast(unsigned, b); }
;     __device__ __forceinline__ void operator()(const f32x4 (&acc)[2][2][4][2], const Unit& u, int wr, int wc, int fr, int fq) const {
;     ...
;         for (int g = 0; g < 8; ++g) { const int ai = g >> 2, m = g & 3; const size_t off = (size_t)(row0 + ai * HALF + m * 16) * 1024 + col0;
;             if (g + 1 < 8) { const int ai2 = (g + 1) >> 2, m2 = (g + 1) & 3; load_x(xv[(g + 1) & 1], (size_t)(row0 + ai2 * HALF + m2 * 16) * 1024 + col0); }
;             float rs_ = 1.0f; if constexpr (ROWSCALE) rs_ = tab[((u.pm == pm0 ? 0 : 256) + ai * HALF + wr * 64 + m * 16 + fr) * 2 + 1];
; #pragma unroll
;             for (int bj = 0; bj < 2; ++bj) { const f32x4 v0 = xv[g & 1][bj][0] + gv[bj][0] * (acc[ai][bj][m][0] * rs_), v1 = xv[g & 1][bj][1] + gv[bj][1] * (acc[ai][bj][m][1] * rs_);
;                 u32x4 w; w.x = cvt_pk_bf16(v0[0], v0[1]); w.y = cvt_pk_bf16(v0[2], v0[3]); w.z = cvt_pk_bf16(v1[0], v1[1]); w.w = cvt_pk_bf16(v1[2], v1[3]);
;                 *(u32x4*)(out + off + bj * HALF) = w; } }
	v_pk_mul_f32 v[112:113], v[112:113], v[204:205] op_sel_hi:[1,0]
	v_pk_mul_f32 v[114:115], v[114:115], v[204:205] op_sel_hi:[1,0]
	v_pk_mul_f32 v[108:109], v[108:109], v[204:205] op_sel_hi:[1,0]
	v_pk_mul_f32 v[110:111], v[110:111], v[204:205] op_sel_hi:[1,0]
	v_pk_fma_f32 v[112:113], v[76:77], v[112:113], v[236:237]
	v_pk_fma_f32 v[114:115], v[78:79], v[114:115], v[238:239]
	v_pk_fma_f32 v[108:109], v[72:73], v[108:109], v[240:241]
	v_pk_fma_f32 v[110:111], v[74:75], v[110:111], v[242:243]
	v_cvt_pk_bf16_f32 v236, v112, v113
	v_cvt_pk_bf16_f32 v237, v114, v115
	v_cvt_pk_bf16_f32 v238, v108, v109
	v_cvt_pk_bf16_f32 v239, v110, v111
	global_store_dwordx4 v195, v[236:239], s[100:101]
	v_pk_mul_f32 v[104:105], v[104:105], v[204:205] op_sel_hi:[1,0]
	v_pk_mul_f32 v[106:107], v[106:107], v[204:205] op_sel_hi:[1,0]
	v_pk_mul_f32 v[100:101], v[100:101], v[204:205] op_sel_hi:[1,0]
	v_pk_mul_f32 v[102:103], v[102:103], v[204:205] op_sel_hi:[1,0]
	v_pk_fma_f32 v[104:105], v[68:69], v[104:105], v[244:245]
	v_pk_fma_f32 v[106:107], v[70:71], v[106:107], v[246:247]
	v_pk_fma_f32 v[100:101], v[64:65], v[100:101], v[248:249]
	v_pk_fma_f32 v[102:103], v[66:67], v[102:103], v[250:251]
	v_cvt_pk_bf16_f32 v244, v104, v105
	v_cvt_pk_bf16_f32 v245, v106, v107
	v_cvt_pk_bf16_f32 v246, v100, v101
	v_cvt_pk_bf16_f32 v247, v102, v103
	global_store_dwordx4 v195, v[244:247], s[100:101] offset:256
	s_add_u32 s100, s100, 0x8000
	s_addc_u32 s101, s101, 0
	global_load_dwordx4 v[236:239], v185, s[98:99]
	global_load_dwordx4 v[240:243], v185, s[98:99] offset:16
	global_load_dwordx4 v[244:247], v185, s[98:99] offset:512
	global_load_dwordx4 v[248:251], v185, s[98:99] offset:528
	s_add_u32 s98, s98, 0x10000
	s_addc_u32 s99, s99, 0
	s_waitcnt vmcnt(12)
	v_pk_mul_f32 v[96:97], v[96:97], v[210:211] op_sel_hi:[1,0]
	v_pk_mul_f32 v[98:99], v[98:99], v[210:211] op_sel_hi:[1,0]
	v_pk_mul_f32 v[92:93], v[92:93], v[210:211] op_sel_hi:[1,0]
	v_pk_mul_f32 v[94:95], v[94:95], v[210:211] op_sel_hi:[1,0]
	v_pk_fma_f32 v[96:97], v[76:77], v[96:97], v[148:149]
	v_pk_fma_f32 v[98:99], v[78:79], v[98:99], v[150:151]
	v_pk_fma_f32 v[92:93], v[72:73], v[92:93], v[152:153]
	v_pk_fma_f32 v[94:95], v[74:75], v[94:95], v[154:155]
	v_cvt_pk_bf16_f32 v148, v96, v97
	v_cvt_pk_bf16_f32 v149, v98, v99
	v_cvt_pk_bf16_f32 v150, v92, v93
	v_cvt_pk_bf16_f32 v151, v94, v95
	global_store_dwordx4 v195, v[148:151], s[100:101]
	v_pk_mul_f32 v[88:89], v[88:89], v[210:211] op_sel_hi:[1,0]
	v_pk_mul_f32 v[90:91], v[90:91], v[210:211] op_sel_hi:[1,0]
	v_pk_mul_f32 v[84:85], v[84:85], v[210:211] op_sel_hi:[1,0]
	v_pk_mul_f32 v[86:87], v[86:87], v[210:211] op_sel_hi:[1,0]
	v_pk_fma_f32 v[88:89], v[68:69], v[88:89], v[180:181]
	v_pk_fma_f32 v[90:91], v[70:71], v[90:91], v[182:183]
	v_pk_fma_f32 v[84:85], v[64:65], v[84:85], v[196:197]
	v_pk_fma_f32 v[86:87], v[66:67], v[86:87], v[198:199]
	v_cvt_pk_bf16_f32 v180, v88, v89
	v_cvt_pk_bf16_f32 v181, v90, v91
	v_cvt_pk_bf16_f32 v182, v84, v85
	v_cvt_pk_bf16_f32 v183, v86, v87
	global_store_dwordx4 v195, v[180:183], s[100:101] offset:256
	s_add_u32 s100, s100, 0x28000
	s_addc_u32 s101, s101, 0
	global_load_dwordx4 v[148:151], v185, s[98:99]
	global_load_dwordx4 v[152:155], v185, s[98:99] offset:16
	global_load_dwordx4 v[180:183], v185, s[98:99] offset:512
	global_load_dwordx4 v[196:199], v185, s[98:99] offset:528
	s_add_u32 s98, s98, 0x10000
	s_addc_u32 s99, s99, 0
	s_waitcnt vmcnt(12)
	v_pk_mul_f32 v[60:61], v[60:61], v[232:233] op_sel_hi:[1,0]
	v_pk_mul_f32 v[62:63], v[62:63], v[232:233] op_sel_hi:[1,0]
	v_pk_mul_f32 v[56:57], v[56:57], v[232:233] op_sel_hi:[1,0]
	v_pk_mul_f32 v[58:59], v[58:59], v[232:233] op_sel_hi:[1,0]
	v_pk_fma_f32 v[60:61], v[76:77], v[60:61], v[200:201]
	v_pk_fma_f32 v[62:63], v[78:79], v[62:63], v[202:203]
	v_pk_fma_f32 v[56:57], v[72:73], v[56:57], v[220:221]
	v_pk_fma_f32 v[58:59], v[74:75], v[58:59], v[222:223]
	v_cvt_pk_bf16_f32 v200, v60, v61
	v_cvt_pk_bf16_f32 v201, v62, v63
	v_cvt_pk_bf16_f32 v202, v56, v57
	v_cvt_pk_bf16_f32 v203, v58, v59
	global_store_dwordx4 v195, v[200:203], s[100:101]
	v_pk_mul_f32 v[52:53], v[52:53], v[232:233] op_sel_hi:[1,0]
	v_pk_mul_f32 v[54:55], v[54:55], v[232:233] op_sel_hi:[1,0]
	v_pk_mul_f32 v[48:49], v[48:49], v[232:233] op_sel_hi:[1,0]
	v_pk_mul_f32 v[50:51], v[50:51], v[232:233] op_sel_hi:[1,0]
	v_pk_fma_f32 v[52:53], v[68:69], v[52:53], v[224:225]
	v_pk_fma_f32 v[54:55], v[70:71], v[54:55], v[226:227]
	v_pk_fma_f32 v[48:49], v[64:65], v[48:49], v[228:229]
	v_pk_fma_f32 v[50:51], v[66:67], v[50:51], v[230:231]
	v_cvt_pk_bf16_f32 v224, v52, v53
	v_cvt_pk_bf16_f32 v225, v54, v55
	v_cvt_pk_bf16_f32 v226, v48, v49
	v_cvt_pk_bf16_f32 v227, v50, v51
	global_store_dwordx4 v195, v[224:227], s[100:101] offset:256
	s_add_u32 s100, s100, 0x8000
	s_addc_u32 s101, s101, 0
	global_load_dwordx4 v[200:203], v185, s[98:99]
	global_load_dwordx4 v[220:223], v185, s[98:99] offset:16
	global_load_dwordx4 v[224:227], v185, s[98:99] offset:512
	global_load_dwordx4 v[228:231], v185, s[98:99] offset:528
	s_add_u32 s98, s98, 0x10000
	s_addc_u32 s99, s99, 0
	s_waitcnt vmcnt(12)
; __device__ __forceinline__ unsigned cvt_pk_bf16(float lo, float hi) { f32x2_cv v = {lo, hi}; bf16x2_cv b = __builtin_convertvector(v, bf16x2_cv); return __builtin_bit_cast(unsigned, b); }
; #define PG8_BAR __builtin_amdgcn_s_barrier()
;     __device__ __forceinline__ void operator()(const f32x4 (&acc)[2][2][4][2], const Unit& u, int wr, int wc, int fr, int fq) const {
;     ...
;             for (int bj = 0; bj < 2; ++bj) { const f32x4 v0 = xv[g & 1][bj][0] + gv[bj][0] * (acc[ai][bj][m][0] * rs_), v1 = xv[g & 1][bj][1] + gv[bj][1] * (acc[ai][bj][m][1] * rs_);
;                 u32x4 w; w.x = cvt_pk_bf16(v0[0], v0[1]); w.y = cvt_pk_bf16(v0[2], v0[3]); w.z = cvt_pk_bf16(v1[0], v1[1]); w.w = cvt_pk_bf16(v1[2], v1[3]);
;                 *(u32x4*)(out + off + bj * HALF) = w; } }
; template <class Epi, class Sched, bool ALIGN_EPI = false, bool SP2 = false, bool MID = false>
; __device__ __forceinline__ void gemm_phase(PG8_LAS unsigned char* lds, const Gemm g, const Sched& S, const Epi& E, const PG8_LAS float* mid = nullptr) {
;     ...
;         if (!has_next) break;
; #pragma unroll
;         for (int a = 0; a < 2; ++a)
; #pragma unroll
;             for (int b = 0; b < 2; ++b)
; #pragma unroll
;                 for (int m = 0; m < 4; ++m)
; #pragma unroll
;                     for (int n = 0; n < 2; ++n) acc[a][b][m][n] = (f32x4){0.f, 0.f, 0.f, 0.f};
;         cur = nxt; cA = nA; cB = nB; ++ui;
;         if constexpr (ALIGN_EPI) { if (wr == 1) PG8_BAR; }
	v_pk_mul_f32 v[44:45], v[44:45], v[234:235] op_sel_hi:[1,0]
	v_pk_mul_f32 v[46:47], v[46:47], v[234:235] op_sel_hi:[1,0]
	v_pk_mul_f32 v[40:41], v[40:41], v[234:235] op_sel_hi:[1,0]
	v_pk_mul_f32 v[42:43], v[42:43], v[234:235] op_sel_hi:[1,0]
	v_pk_fma_f32 v[44:45], v[76:77], v[44:45], v[236:237]
	v_pk_fma_f32 v[46:47], v[78:79], v[46:47], v[238:239]
	v_pk_fma_f32 v[40:41], v[72:73], v[40:41], v[240:241]
	v_pk_fma_f32 v[42:43], v[74:75], v[42:43], v[242:243]
	v_cvt_pk_bf16_f32 v236, v44, v45
	v_cvt_pk_bf16_f32 v237, v46, v47
	v_cvt_pk_bf16_f32 v238, v40, v41
	v_cvt_pk_bf16_f32 v239, v42, v43
	global_store_dwordx4 v195, v[236:239], s[100:101]
	v_pk_mul_f32 v[36:37], v[36:37], v[234:235] op_sel_hi:[1,0]
	v_pk_mul_f32 v[38:39], v[38:39], v[234:235] op_sel_hi:[1,0]
	v_pk_mul_f32 v[32:33], v[32:33], v[234:235] op_sel_hi:[1,0]
	v_pk_mul_f32 v[34:35], v[34:35], v[234:235] op_sel_hi:[1,0]
	v_pk_fma_f32 v[36:37], v[68:69], v[36:37], v[244:245]
	v_pk_fma_f32 v[38:39], v[70:71], v[38:39], v[246:247]
	v_pk_fma_f32 v[32:33], v[64:65], v[32:33], v[248:249]
	v_pk_fma_f32 v[34:35], v[66:67], v[34:35], v[250:251]
	v_cvt_pk_bf16_f32 v244, v36, v37
	v_cvt_pk_bf16_f32 v245, v38, v39
	v_cvt_pk_bf16_f32 v246, v32, v33
	v_cvt_pk_bf16_f32 v247, v34, v35
	global_store_dwordx4 v195, v[244:247], s[100:101] offset:256
	s_add_u32 s100, s100, 0x8000
	s_addc_u32 s101, s101, 0
	s_waitcnt vmcnt(8)
	v_pk_mul_f32 v[28:29], v[28:29], v[82:83] op_sel_hi:[1,0]
	v_pk_mul_f32 v[30:31], v[30:31], v[82:83] op_sel_hi:[1,0]
	v_pk_mul_f32 v[24:25], v[24:25], v[82:83] op_sel_hi:[1,0]
	v_pk_mul_f32 v[26:27], v[26:27], v[82:83] op_sel_hi:[1,0]
	v_pk_fma_f32 v[28:29], v[76:77], v[28:29], v[148:149]
	v_pk_fma_f32 v[30:31], v[78:79], v[30:31], v[150:151]
	v_pk_fma_f32 v[24:25], v[72:73], v[24:25], v[152:153]
	v_pk_fma_f32 v[26:27], v[74:75], v[26:27], v[154:155]
	v_cvt_pk_bf16_f32 v148, v28, v29
	v_cvt_pk_bf16_f32 v149, v30, v31
	v_cvt_pk_bf16_f32 v150, v24, v25
	v_cvt_pk_bf16_f32 v151, v26, v27
	global_store_dwordx4 v195, v[148:151], s[100:101]
	v_pk_mul_f32 v[20:21], v[20:21], v[82:83] op_sel_hi:[1,0]
	v_pk_mul_f32 v[22:23], v[22:23], v[82:83] op_sel_hi:[1,0]
	v_pk_mul_f32 v[16:17], v[16:17], v[82:83] op_sel_hi:[1,0]
	v_pk_mul_f32 v[18:19], v[18:19], v[82:83] op_sel_hi:[1,0]
	v_pk_fma_f32 v[20:21], v[68:69], v[20:21], v[180:181]
	v_pk_fma_f32 v[22:23], v[70:71], v[22:23], v[182:183]
	v_pk_fma_f32 v[16:17], v[64:65], v[16:17], v[196:197]
	v_pk_fma_f32 v[18:19], v[66:67], v[18:19], v[198:199]
	v_cvt_pk_bf16_f32 v180, v20, v21
	v_cvt_pk_bf16_f32 v181, v22, v23
	v_cvt_pk_bf16_f32 v182, v16, v17
	v_cvt_pk_bf16_f32 v183, v18, v19
	global_store_dwordx4 v195, v[180:183], s[100:101] offset:256
	s_add_u32 s100, s100, 0x8000
	s_addc_u32 s101, s101, 0
	s_waitcnt vmcnt(4)
	v_pk_mul_f32 v[12:13], v[12:13], v[80:81] op_sel_hi:[1,0]
	v_pk_mul_f32 v[14:15], v[14:15], v[80:81] op_sel_hi:[1,0]
	v_pk_mul_f32 v[8:9], v[8:9], v[80:81] op_sel_hi:[1,0]
	v_pk_mul_f32 v[10:11], v[10:11], v[80:81] op_sel_hi:[1,0]
	v_pk_fma_f32 v[12:13], v[76:77], v[12:13], v[200:201]
	v_pk_fma_f32 v[14:15], v[78:79], v[14:15], v[202:203]
	v_pk_fma_f32 v[8:9], v[72:73], v[8:9], v[220:221]
	v_pk_fma_f32 v[10:11], v[74:75], v[10:11], v[222:223]
	v_cvt_pk_bf16_f32 v200, v12, v13
	v_cvt_pk_bf16_f32 v201, v14, v15
	v_cvt_pk_bf16_f32 v202, v8, v9
	v_cvt_pk_bf16_f32 v203, v10, v11
	global_store_dwordx4 v195, v[200:203], s[100:101]
	v_pk_mul_f32 v[4:5], v[4:5], v[80:81] op_sel_hi:[1,0]
	v_pk_mul_f32 v[6:7], v[6:7], v[80:81] op_sel_hi:[1,0]
	v_pk_mul_f32 v[0:1], v[0:1], v[80:81] op_sel_hi:[1,0]
	v_pk_mul_f32 v[2:3], v[2:3], v[80:81] op_sel_hi:[1,0]
	v_pk_fma_f32 v[4:5], v[68:69], v[4:5], v[224:225]
	v_pk_fma_f32 v[6:7], v[70:71], v[6:7], v[226:227]
	v_pk_fma_f32 v[0:1], v[64:65], v[0:1], v[228:229]
	v_pk_fma_f32 v[2:3], v[66:67], v[2:3], v[230:231]
	v_cvt_pk_bf16_f32 v224, v4, v5
	v_cvt_pk_bf16_f32 v225, v6, v7
	v_cvt_pk_bf16_f32 v226, v0, v1
	v_cvt_pk_bf16_f32 v227, v2, v3
	global_store_dwordx4 v195, v[224:227], s[100:101] offset:256
	s_add_u32 s100, s100, 0x8000
	s_addc_u32 s101, s101, 0
	s_mov_b64 s[4:5], -1
	s_cbranch_vccnz .LBB0_432
	s_andn2_b64 vcc, exec, s[40:41]
	s_cbranch_vccnz .LBB0_431
	s_barrier
	s_branch .LBB0_431
